# residual GEMM phases (Wout, Down): workgroups 128-255 start ~15 us late so their bandwidth-bound f32 epilogues overlap the other half's K-loops
# baseline (speedup 1.0000x reference)
; #define LAS __attribute__((address_space(3)))
; DI int oidx(int i) { asm volatile("" : "+s"(i)); return i; }
;   DI bool next(int i, pg8::Unit& u) const {
;     const long L = (long)i * G + c; if (L >= nwg) return false;
;     int wgid = (int)L; { const int q = nwg / pg8::NXCD, r = nwg % pg8::NXCD, xcd = wgid % pg8::NXCD, off = wgid / pg8::NXCD; wgid = (xcd < r ? xcd * (q + 1) : r * (q + 1) + (xcd - r) * q) + off; }
;     const int nig = pg8::WGM * nN, gid = wgid / nig, fm = gid * pg8::WGM, gsz = (nM - fm) < pg8::WGM ? (nM - fm) : pg8::WGM;
;     const int pm = fm + ((wgid % nig) % gsz); u.pn = (wgid % nig) / gsz;
;     u.pm = skip ? (pm >> 3) * 9 + (pm & 7) : pm;
; DN void phase_resid_gemm(const Params& p, int l, const bfr* A, const bfr* Bt, int K, int gi, bool src_input, bool skip_ctx) {
;   pg8::Gemm g; g.A = A; g.Bt = Bt; g.M = MR; g.N = DM; g.K = K;
;   MySched S; S.init(skip_ctx ? 128 : 144, 4, gridDim.x, blockIdx.x, skip_ctx);
;   EpiResid E; E.xin = p.in[oidx(0)]; E.cin = p.in[oidx(2)]; E.xout = p.out; E.xc = (float*)(p.ws + OFF_XC);
;   E.modl = (const float*)(p.ws + OFF_MOD) + (size_t)l * 17 * 6144; E.gi = gi; E.src_input = src_input;
;   pg8::gemm_phase<EpiResid, MySched, true, true>((LAS unsigned char*)dynlds, g, S, E);
; }
.LBB0_1121:
	s_or_b64 exec, exec, s[2:3]
	s_and_b64 s[2:3], s[92:93], exec
	s_mov_b32 s2, s81
	s_barrier
	s_cselect_b32 s68, s97, 0x80
	v_readlane_b32 s98, v252, 0
	s_nop 3
	s_cmpk_lt_u32 s98, 0x80
	s_cbranch_scc1 .Lstag_wout
	s_sleep 127
	s_sleep 127
	s_sleep 127
	s_sleep 127
.Lstag_wout:
	s_ashr_i32 s3, s2, 31
	s_lshl_b32 s80, s68, 2
	s_lshl_b64 s[2:3], s[2:3], 3
	s_add_u32 s2, s0, s2
	s_addc_u32 s3, s1, s3
	s_load_dwordx2 s[12:13], s[2:3], 0x0
	s_mov_b32 s2, 2
	s_ashr_i32 s3, s2, 31
	s_lshl_b64 s[2:3], s[2:3], 3
	s_add_u32 s2, s0, s2
	s_addc_u32 s3, s1, s3
	s_load_dwordx2 s[14:15], s[2:3], 0x0
	v_readlane_b32 s4, v252, 0
	v_mov_b32_e32 v8, v182
	s_cmp_lt_i32 s4, s80
	s_cselect_b64 s[2:3], -1, 0
	s_cmp_ge_i32 s4, s80
	v_readfirstlane_b32 s18, v8
	s_cbranch_scc1 .LBB0_1123
	s_lshr_b32 s4, s68, 1
	v_readlane_b32 s5, v252, 40
	s_or_b32 s4, s4, s5
	v_readlane_b32 s5, v252, 39
	s_mul_i32 s4, s4, s5
	v_readlane_b32 s5, v252, 29
	s_add_i32 s4, s4, s5
	s_ashr_i32 s5, s4, 31
	s_lshr_b32 s5, s5, 27
	s_add_i32 s5, s4, s5
	s_ashr_i32 s6, s5, 5
	s_lshl_b32 s6, s6, 3
	s_sub_i32 s7, s68, s6
	s_min_i32 s7, s7, 8
	v_cvt_f32_i32_e32 v0, s7
	s_andn2_b32 s5, s5, 31
	s_sub_i32 s8, s4, s5
	v_cvt_f32_i32_e32 v1, s8
	v_rcp_iflag_f32_e32 v2, v0
	s_xor_b32 s4, s8, s7
	s_ashr_i32 s4, s4, 30
	s_or_b32 s9, s4, 1
	v_mul_f32_e32 v2, v1, v2
	v_trunc_f32_e32 v2, v2
	v_fma_f32 v1, -v2, v0, v1
	v_cvt_i32_f32_e32 v2, v2
	v_cmp_ge_f32_e64 s[4:5], |v1|, |v0|
	s_and_b64 s[4:5], s[4:5], exec
	s_cselect_b32 s4, s9, 0
	v_readfirstlane_b32 s5, v2
	s_add_i32 s4, s5, s4
	s_sext_i32_i8 s30, s4
	s_mul_i32 s4, s4, s7
	s_sub_i32 s4, s8, s4
	s_sext_i32_i8 s4, s4
	s_add_i32 s6, s6, s4
	s_ashr_i32 s5, s6, 3
	s_mul_i32 s5, s5, 9
	s_and_b32 s4, s4, 7
	s_add_i32 s7, s5, s4
	s_and_b64 s[4:5], s[92:93], exec
	s_cselect_b32 s4, s6, s7

; DI int oidx(int i) { asm volatile("" : "+s"(i)); return i; }
; DN void fix_own_tiles(const Params& p, int l, bool skip_ctx) {
;   bfr* A2 = (bfr*)(p.ws + OFF_A2);
;   const float* EDGE = (const float*)(p.ws + OFF_EDGE);
;   const float* cw = p.in[oidx(29)] + (size_t)l * 3 * DFF;
;   MySched S; S.init(skip_ctx ? 128 : 144, 4, gridDim.x, blockIdx.x, skip_ctx);
;   int tid_ = threadIdx.x; asm volatile("" : "+v"(tid_));
;   pg8::Unit u;
;   for (int ui = 0; S.next(ui, u); ++ui) {
;     const int tile = u.pm, m0 = tile * 256, t0 = m0 % TT;
;     for (int i = tid_; i < 2 * DFF; i += 512) {
.LBB0_1481:
	s_or_b64 exec, exec, s[2:3]
	s_mov_b32 s2, 29
	s_barrier
	v_readlane_b32 s98, v252, 0
	s_nop 3
	s_cmpk_lt_u32 s98, 0x80
	s_cbranch_scc1 .Lstag_down
	s_sleep 127
	s_sleep 127
	s_sleep 127
	s_sleep 127
.Lstag_down:
	s_ashr_i32 s3, s2, 31
	s_lshl_b64 s[2:3], s[2:3], 3
	s_add_u32 s2, s0, s2
	s_addc_u32 s3, s1, s3
	s_load_dwordx2 s[2:3], s[2:3], 0x0
	v_readlane_b32 s4, v253, 13
	s_mulk_i32 s4, 0x2100
	s_mov_b32 s5, s81
	s_lshl_b64 s[4:5], s[4:5], 2
	s_waitcnt lgkmcnt(0)
	s_add_u32 s10, s2, s4
	v_mov_b32_e32 v0, v182
	s_movk_i32 s2, 0x1600
	s_addc_u32 s11, s3, s5
	s_lshr_b32 s18, s68, 1
	v_cmp_gt_i32_e64 s[2:3], s2, v0
	s_mov_b32 s19, 0
	s_branch .LBB0_1484
